# tile epilogues without the priority raise for the leading wave half
# speedup vs baseline: 1.0050x; 1.0050x over previous
.Lg131_mid:
	ds_read_b128 v[152:155], v164
	ds_read_b128 v[156:159], v164 offset:1024
	ds_read_b128 v[160:163], v164 offset:2048
	ds_read_b128 v[164:167], v164 offset:3072
	s_add_u32 s28, s28, 0x40000
	s_addc_u32 s29, s29, 0
	s_mov_b32 m0, s43
	ds_read_b128 v[168:171], v150 offset:32768
	ds_read_b128 v[172:175], v150 offset:33792
	ds_read_b128 v[176:179], v150 offset:34816
	ds_read_b128 v[180:183], v150 offset:35840
	ds_read_b128 v[184:187], v150 offset:36864
	ds_read_b128 v[188:191], v150 offset:37888
	ds_read_b128 v[192:195], v150 offset:38912
	ds_read_b128 v[196:199], v150 offset:39936
	global_load_lds_dwordx4 v134, s[28:29]
	s_mov_b32 m0, s44
	s_nop 0
	global_load_lds_dwordx4 v130, s[28:29]
	s_waitcnt lgkmcnt(8)
	s_barrier
	s_waitcnt lgkmcnt(0)
	s_waitcnt lgkmcnt(0)
	v_mfma_f32_16x16x32_bf16 v[124:127], v[152:155], v[168:171], v[124:127]
	v_mfma_f32_16x16x32_bf16 v[120:123], v[160:163], v[168:171], v[120:123]
	v_mfma_f32_16x16x32_bf16 v[108:111], v[152:155], v[176:179], v[108:111]
	v_mfma_f32_16x16x32_bf16 v[104:107], v[160:163], v[176:179], v[104:107]
	v_mfma_f32_16x16x32_bf16 v[92:95], v[152:155], v[184:187], v[92:95]
	v_mfma_f32_16x16x32_bf16 v[88:91], v[160:163], v[184:187], v[88:91]
	v_mfma_f32_16x16x32_bf16 v[76:79], v[152:155], v[192:195], v[76:79]
	v_mfma_f32_16x16x32_bf16 v[72:75], v[160:163], v[192:195], v[72:75]
	v_mfma_f32_16x16x32_bf16 v[124:127], v[156:159], v[172:175], v[124:127]
	v_mfma_f32_16x16x32_bf16 v[120:123], v[164:167], v[172:175], v[120:123]
	v_mfma_f32_16x16x32_bf16 v[108:111], v[156:159], v[180:183], v[108:111]
	v_mfma_f32_16x16x32_bf16 v[104:107], v[164:167], v[180:183], v[104:107]
	v_mfma_f32_16x16x32_bf16 v[92:95], v[156:159], v[188:191], v[92:95]
	v_mfma_f32_16x16x32_bf16 v[88:91], v[164:167], v[188:191], v[88:91]
	v_mfma_f32_16x16x32_bf16 v[76:79], v[156:159], v[196:199], v[76:79]
	v_mfma_f32_16x16x32_bf16 v[72:75], v[164:167], v[196:199], v[72:75]
	s_barrier
	s_add_i32 s28, 0, 0x1c000
	s_add_i32 s29, s58, s38
	v_add_u32_e32 v212, s28, v145
	s_mov_b32 m0, s29
	ds_read_b128 v[200:203], v212
	ds_read_b128 v[204:207], v212 offset:1024
	ds_read_b128 v[208:211], v212 offset:2048
	ds_read_b128 v[212:215], v212 offset:3072
	global_load_lds_dwordx4 v132, s[80:81]
	s_add_i32 m0, s29, 0x2000
	s_nop 0
	global_load_lds_dwordx4 v128, s[80:81]
	s_waitcnt vmcnt(10)
	s_barrier
	s_waitcnt lgkmcnt(0)
	s_waitcnt lgkmcnt(0)
	v_mfma_f32_16x16x32_bf16 v[116:119], v[200:203], v[168:171], v[116:119]
	v_mfma_f32_16x16x32_bf16 v[112:115], v[208:211], v[168:171], v[112:115]
	v_mfma_f32_16x16x32_bf16 v[100:103], v[200:203], v[176:179], v[100:103]
	v_mfma_f32_16x16x32_bf16 v[96:99], v[208:211], v[176:179], v[96:99]
	v_mfma_f32_16x16x32_bf16 v[84:87], v[200:203], v[184:187], v[84:87]
	v_mfma_f32_16x16x32_bf16 v[80:83], v[208:211], v[184:187], v[80:83]
	v_mfma_f32_16x16x32_bf16 v[68:71], v[200:203], v[192:195], v[68:71]
	v_mfma_f32_16x16x32_bf16 v[64:67], v[208:211], v[192:195], v[64:67]
	v_mfma_f32_16x16x32_bf16 v[116:119], v[204:207], v[172:175], v[116:119]
	v_mfma_f32_16x16x32_bf16 v[112:115], v[212:215], v[172:175], v[112:115]
	v_mfma_f32_16x16x32_bf16 v[100:103], v[204:207], v[180:183], v[100:103]
	v_mfma_f32_16x16x32_bf16 v[96:99], v[212:215], v[180:183], v[96:99]
	v_mfma_f32_16x16x32_bf16 v[84:87], v[204:207], v[188:191], v[84:87]
	v_mfma_f32_16x16x32_bf16 v[80:83], v[212:215], v[188:191], v[80:83]
	v_mfma_f32_16x16x32_bf16 v[68:71], v[204:207], v[196:199], v[68:71]
	v_mfma_f32_16x16x32_bf16 v[64:67], v[212:215], v[196:199], v[64:67]
	s_mov_b32 m0, s45
	s_barrier
	ds_read_b128 v[168:171], v150 offset:49152
	ds_read_b128 v[172:175], v150 offset:50176
	ds_read_b128 v[176:179], v150 offset:51200
	ds_read_b128 v[180:183], v150 offset:52224
	ds_read_b128 v[184:187], v150 offset:53248
	ds_read_b128 v[188:191], v150 offset:54272
	ds_read_b128 v[192:195], v150 offset:55296
	ds_read_b128 v[196:199], v150 offset:56320
	global_load_lds_dwordx4 v134, s[82:83]
	s_mov_b32 m0, s46
	s_nop 0
	global_load_lds_dwordx4 v130, s[82:83]
	s_barrier
	s_waitcnt lgkmcnt(0)
	s_waitcnt lgkmcnt(0)
	v_mfma_f32_16x16x32_bf16 v[60:63], v[152:155], v[168:171], v[60:63]
	v_mfma_f32_16x16x32_bf16 v[56:59], v[160:163], v[168:171], v[56:59]
	v_mfma_f32_16x16x32_bf16 v[44:47], v[152:155], v[176:179], v[44:47]
	v_mfma_f32_16x16x32_bf16 v[40:43], v[160:163], v[176:179], v[40:43]
	v_mfma_f32_16x16x32_bf16 v[28:31], v[152:155], v[184:187], v[28:31]
	v_mfma_f32_16x16x32_bf16 v[24:27], v[160:163], v[184:187], v[24:27]
	v_mfma_f32_16x16x32_bf16 v[12:15], v[152:155], v[192:195], v[12:15]
	v_mfma_f32_16x16x32_bf16 v[8:11], v[160:163], v[192:195], v[8:11]
	v_mfma_f32_16x16x32_bf16 v[60:63], v[156:159], v[172:175], v[60:63]
	v_mfma_f32_16x16x32_bf16 v[56:59], v[164:167], v[172:175], v[56:59]
	v_mfma_f32_16x16x32_bf16 v[44:47], v[156:159], v[180:183], v[44:47]
	v_mfma_f32_16x16x32_bf16 v[40:43], v[164:167], v[180:183], v[40:43]
	v_mfma_f32_16x16x32_bf16 v[28:31], v[156:159], v[188:191], v[28:31]
	v_mfma_f32_16x16x32_bf16 v[24:27], v[164:167], v[188:191], v[24:27]
	v_mfma_f32_16x16x32_bf16 v[12:15], v[156:159], v[196:199], v[12:15]
	v_mfma_f32_16x16x32_bf16 v[8:11], v[164:167], v[196:199], v[8:11]
	s_barrier
	s_add_u32 s26, s26, 0x40080
	s_addc_u32 s27, s27, 0
	s_add_i32 s28, s28, s38
	s_mov_b32 m0, s28
	s_nop 0
	global_load_lds_dwordx4 v132, s[26:27]
	s_add_i32 m0, s28, 0x2000
	s_nop 0
	global_load_lds_dwordx4 v128, s[26:27]
	s_waitcnt vmcnt(8)
	s_barrier
	v_mfma_f32_16x16x32_bf16 v[52:55], v[200:203], v[168:171], v[52:55]
	v_mfma_f32_16x16x32_bf16 v[48:51], v[208:211], v[168:171], v[48:51]
	v_mfma_f32_16x16x32_bf16 v[36:39], v[200:203], v[176:179], v[36:39]
	v_mfma_f32_16x16x32_bf16 v[32:35], v[208:211], v[176:179], v[32:35]
	v_mfma_f32_16x16x32_bf16 v[20:23], v[200:203], v[184:187], v[20:23]
	v_mfma_f32_16x16x32_bf16 v[16:19], v[208:211], v[184:187], v[16:19]
	v_mfma_f32_16x16x32_bf16 v[4:7], v[200:203], v[192:195], v[4:7]
	v_mfma_f32_16x16x32_bf16 v[0:3], v[208:211], v[192:195], v[0:3]
	v_mfma_f32_16x16x32_bf16 v[52:55], v[204:207], v[172:175], v[52:55]
	v_mfma_f32_16x16x32_bf16 v[48:51], v[212:215], v[172:175], v[48:51]
	v_mfma_f32_16x16x32_bf16 v[36:39], v[204:207], v[180:183], v[36:39]
	v_mfma_f32_16x16x32_bf16 v[32:35], v[212:215], v[180:183], v[32:35]
	v_mfma_f32_16x16x32_bf16 v[20:23], v[204:207], v[188:191], v[20:23]
	v_mfma_f32_16x16x32_bf16 v[16:19], v[212:215], v[188:191], v[16:19]
	v_mfma_f32_16x16x32_bf16 v[4:7], v[204:207], v[196:199], v[4:7]
	v_mfma_f32_16x16x32_bf16 v[0:3], v[212:215], v[196:199], v[0:3]
	s_add_i32 s57, s57, 2
	s_add_u32 s20, s20, 0x100
	s_addc_u32 s21, s21, 0
	s_add_u32 s55, s55, 0x100
	s_addc_u32 s56, s56, 0
	s_cmp_gt_u32 s57, 13
	s_barrier
	s_cbranch_scc0 .LBB0_131
	s_setprio 0
	s_cmpk_gt_u32 s37, 0xff
	s_cbranch_scc1 .Lg131_nox
	s_barrier
	s_nop 0

.Lg248_mid:
	ds_read_b128 v[144:147], v155
	ds_read_b128 v[156:159], v155 offset:1024
	ds_read_b128 v[160:163], v155 offset:2048
	ds_read_b128 v[164:167], v155 offset:3072
	s_add_u32 s20, s30, 0xb0000
	s_addc_u32 s21, s31, 0
	s_mov_b32 m0, s43
	ds_read_b128 v[168:171], v152 offset:32768
	ds_read_b128 v[172:175], v152 offset:33792
	ds_read_b128 v[176:179], v152 offset:34816
	ds_read_b128 v[180:183], v152 offset:35840
	ds_read_b128 v[184:187], v152 offset:36864
	ds_read_b128 v[188:191], v152 offset:37888
	ds_read_b128 v[192:195], v152 offset:38912
	ds_read_b128 v[196:199], v152 offset:39936
	global_load_lds_dwordx4 v128, s[20:21]
	s_mov_b32 m0, s44
	s_nop 0
	global_load_lds_dwordx4 v132, s[20:21]
	s_waitcnt lgkmcnt(8)
	s_barrier
	s_waitcnt lgkmcnt(0)
	s_waitcnt lgkmcnt(0)
	v_mfma_f32_16x16x32_bf16 v[124:127], v[144:147], v[168:171], v[124:127]
	v_mfma_f32_16x16x32_bf16 v[120:123], v[160:163], v[168:171], v[120:123]
	v_mfma_f32_16x16x32_bf16 v[108:111], v[144:147], v[176:179], v[108:111]
	v_mfma_f32_16x16x32_bf16 v[104:107], v[160:163], v[176:179], v[104:107]
	v_mfma_f32_16x16x32_bf16 v[92:95], v[144:147], v[184:187], v[92:95]
	v_mfma_f32_16x16x32_bf16 v[88:91], v[160:163], v[184:187], v[88:91]
	v_mfma_f32_16x16x32_bf16 v[76:79], v[144:147], v[192:195], v[76:79]
	v_mfma_f32_16x16x32_bf16 v[72:75], v[160:163], v[192:195], v[72:75]
	v_mfma_f32_16x16x32_bf16 v[124:127], v[156:159], v[172:175], v[124:127]
	v_mfma_f32_16x16x32_bf16 v[120:123], v[164:167], v[172:175], v[120:123]
	v_mfma_f32_16x16x32_bf16 v[108:111], v[156:159], v[180:183], v[108:111]
	v_mfma_f32_16x16x32_bf16 v[104:107], v[164:167], v[180:183], v[104:107]
	v_mfma_f32_16x16x32_bf16 v[92:95], v[156:159], v[188:191], v[92:95]
	v_mfma_f32_16x16x32_bf16 v[88:91], v[164:167], v[188:191], v[88:91]
	v_mfma_f32_16x16x32_bf16 v[76:79], v[156:159], v[196:199], v[76:79]
	v_mfma_f32_16x16x32_bf16 v[72:75], v[164:167], v[196:199], v[72:75]
	s_barrier
	s_add_i32 s30, 0, 0x1c000
	s_add_i32 s20, s60, s40
	v_add_u32_e32 v155, s30, v149
	s_mov_b32 m0, s20
	ds_read_b128 v[200:203], v155
	ds_read_b128 v[204:207], v155 offset:1024
	ds_read_b128 v[208:211], v155 offset:2048
	ds_read_b128 v[212:215], v155 offset:3072
	global_load_lds_dwordx4 v130, s[80:81]
	s_add_i32 m0, s20, 0x2000
	s_nop 0
	global_load_lds_dwordx4 v134, s[80:81]
	s_waitcnt vmcnt(10)
	s_barrier
	s_waitcnt lgkmcnt(0)
	s_waitcnt lgkmcnt(0)
	v_mfma_f32_16x16x32_bf16 v[116:119], v[200:203], v[168:171], v[116:119]
	v_mfma_f32_16x16x32_bf16 v[112:115], v[208:211], v[168:171], v[112:115]
	v_mfma_f32_16x16x32_bf16 v[100:103], v[200:203], v[176:179], v[100:103]
	v_mfma_f32_16x16x32_bf16 v[96:99], v[208:211], v[176:179], v[96:99]
	v_mfma_f32_16x16x32_bf16 v[84:87], v[200:203], v[184:187], v[84:87]
	v_mfma_f32_16x16x32_bf16 v[80:83], v[208:211], v[184:187], v[80:83]
	v_mfma_f32_16x16x32_bf16 v[68:71], v[200:203], v[192:195], v[68:71]
	v_mfma_f32_16x16x32_bf16 v[64:67], v[208:211], v[192:195], v[64:67]
	v_mfma_f32_16x16x32_bf16 v[116:119], v[204:207], v[172:175], v[116:119]
	v_mfma_f32_16x16x32_bf16 v[112:115], v[212:215], v[172:175], v[112:115]
	v_mfma_f32_16x16x32_bf16 v[100:103], v[204:207], v[180:183], v[100:103]
	v_mfma_f32_16x16x32_bf16 v[96:99], v[212:215], v[180:183], v[96:99]
	v_mfma_f32_16x16x32_bf16 v[84:87], v[204:207], v[188:191], v[84:87]
	v_mfma_f32_16x16x32_bf16 v[80:83], v[212:215], v[188:191], v[80:83]
	v_mfma_f32_16x16x32_bf16 v[68:71], v[204:207], v[196:199], v[68:71]
	v_mfma_f32_16x16x32_bf16 v[64:67], v[212:215], v[196:199], v[64:67]
	s_mov_b32 m0, s46
	s_barrier
	ds_read_b128 v[168:171], v152 offset:49152
	ds_read_b128 v[172:175], v152 offset:50176
	ds_read_b128 v[176:179], v152 offset:51200
	ds_read_b128 v[180:183], v152 offset:52224
	ds_read_b128 v[184:187], v152 offset:53248
	ds_read_b128 v[188:191], v152 offset:54272
	ds_read_b128 v[192:195], v152 offset:55296
	ds_read_b128 v[196:199], v152 offset:56320
	global_load_lds_dwordx4 v128, s[82:83]
	s_mov_b32 m0, s47
	s_nop 0
	global_load_lds_dwordx4 v132, s[82:83]
	s_barrier
	s_waitcnt lgkmcnt(0)
	s_waitcnt lgkmcnt(0)
	v_mfma_f32_16x16x32_bf16 v[60:63], v[144:147], v[168:171], v[60:63]
	v_mfma_f32_16x16x32_bf16 v[56:59], v[160:163], v[168:171], v[56:59]
	v_mfma_f32_16x16x32_bf16 v[44:47], v[144:147], v[176:179], v[44:47]
	v_mfma_f32_16x16x32_bf16 v[40:43], v[160:163], v[176:179], v[40:43]
	v_mfma_f32_16x16x32_bf16 v[28:31], v[144:147], v[184:187], v[28:31]
	v_mfma_f32_16x16x32_bf16 v[24:27], v[160:163], v[184:187], v[24:27]
	v_mfma_f32_16x16x32_bf16 v[12:15], v[144:147], v[192:195], v[12:15]
	v_mfma_f32_16x16x32_bf16 v[8:11], v[160:163], v[192:195], v[8:11]
	v_mfma_f32_16x16x32_bf16 v[60:63], v[156:159], v[172:175], v[60:63]
	v_mfma_f32_16x16x32_bf16 v[56:59], v[164:167], v[172:175], v[56:59]
	v_mfma_f32_16x16x32_bf16 v[44:47], v[156:159], v[180:183], v[44:47]
	v_mfma_f32_16x16x32_bf16 v[40:43], v[164:167], v[180:183], v[40:43]
	v_mfma_f32_16x16x32_bf16 v[28:31], v[156:159], v[188:191], v[28:31]
	v_mfma_f32_16x16x32_bf16 v[24:27], v[164:167], v[188:191], v[24:27]
	v_mfma_f32_16x16x32_bf16 v[12:15], v[156:159], v[196:199], v[12:15]
	v_mfma_f32_16x16x32_bf16 v[8:11], v[164:167], v[196:199], v[8:11]
	s_barrier
	s_add_u32 s20, s28, 0xb0080
	s_addc_u32 s21, s29, 0
	s_add_i32 s28, s30, s40
	s_mov_b32 m0, s28
	s_nop 0
	global_load_lds_dwordx4 v130, s[20:21]
	s_add_i32 m0, s28, 0x2000
	s_nop 0
	global_load_lds_dwordx4 v134, s[20:21]
	s_waitcnt vmcnt(8)
	s_barrier
	v_mfma_f32_16x16x32_bf16 v[52:55], v[200:203], v[168:171], v[52:55]
	v_mfma_f32_16x16x32_bf16 v[48:51], v[208:211], v[168:171], v[48:51]
	v_mfma_f32_16x16x32_bf16 v[36:39], v[200:203], v[176:179], v[36:39]
	v_mfma_f32_16x16x32_bf16 v[32:35], v[208:211], v[176:179], v[32:35]
	v_mfma_f32_16x16x32_bf16 v[20:23], v[200:203], v[184:187], v[20:23]
	v_mfma_f32_16x16x32_bf16 v[16:19], v[208:211], v[184:187], v[16:19]
	v_mfma_f32_16x16x32_bf16 v[4:7], v[200:203], v[192:195], v[4:7]
	v_mfma_f32_16x16x32_bf16 v[0:3], v[208:211], v[192:195], v[0:3]
	v_mfma_f32_16x16x32_bf16 v[52:55], v[204:207], v[172:175], v[52:55]
	v_mfma_f32_16x16x32_bf16 v[48:51], v[212:215], v[172:175], v[48:51]
	v_mfma_f32_16x16x32_bf16 v[36:39], v[204:207], v[180:183], v[36:39]
	v_mfma_f32_16x16x32_bf16 v[32:35], v[212:215], v[180:183], v[32:35]
	v_mfma_f32_16x16x32_bf16 v[20:23], v[204:207], v[188:191], v[20:23]
	v_mfma_f32_16x16x32_bf16 v[16:19], v[212:215], v[188:191], v[16:19]
	v_mfma_f32_16x16x32_bf16 v[4:7], v[204:207], v[196:199], v[4:7]
	v_mfma_f32_16x16x32_bf16 v[0:3], v[212:215], v[196:199], v[0:3]
	s_add_i32 s59, s59, 2
	s_add_u32 s57, s57, 0x100
	s_addc_u32 s58, s58, 0
	s_cmp_gt_u32 s59, 41
	s_mov_b64 s[20:21], s[26:27]
	s_barrier
	s_cbranch_scc0 .LBB0_248
	s_setprio 0
	v_lshl_add_u32 v146, s56, 8, v148
	v_ashrrev_i32_e32 v147, 31, v146
	v_lshl_or_b32 v144, s12, 8, v150
	v_lshlrev_b64 v[156:157], 11, v[146:147]
	v_ashrrev_i32_e32 v145, 31, v144
	v_lshl_add_u64 v[156:157], s[14:15], 0, v[156:157]
	v_lshl_add_u64 v[166:167], v[144:145], 1, v[156:157]
	global_load_dwordx4 v[158:161], v[166:167], off
	global_load_dwordx4 v[162:165], v[166:167], off offset:256
	s_mov_b64 s[84:85], 0x8000
	s_mov_b64 s[86:87], 0x28000
	v_lshl_add_u64 v[232:233], v[166:167], 0, s[84:85]
	global_load_dwordx4 v[176:179], v[232:233], off
	global_load_dwordx4 v[180:183], v[232:233], off offset:256
	v_lshl_add_u64 v[232:233], v[232:233], 0, s[84:85]
	global_load_dwordx4 v[184:187], v[232:233], off
	global_load_dwordx4 v[188:191], v[232:233], off offset:256
	v_lshl_add_u64 v[232:233], v[232:233], 0, s[84:85]
	global_load_dwordx4 v[192:195], v[232:233], off
	global_load_dwordx4 v[196:199], v[232:233], off offset:256
	v_lshl_add_u64 v[232:233], v[232:233], 0, s[86:87]
	global_load_dwordx4 v[200:203], v[232:233], off
	global_load_dwordx4 v[204:207], v[232:233], off offset:256
	v_lshl_add_u64 v[232:233], v[232:233], 0, s[84:85]
	global_load_dwordx4 v[208:211], v[232:233], off
	global_load_dwordx4 v[212:215], v[232:233], off offset:256
	v_lshl_add_u64 v[232:233], v[232:233], 0, s[84:85]
	global_load_dwordx4 v[216:219], v[232:233], off
	global_load_dwordx4 v[220:223], v[232:233], off offset:256
	v_lshl_add_u64 v[232:233], v[232:233], 0, s[84:85]
	global_load_dwordx4 v[224:227], v[232:233], off
	global_load_dwordx4 v[228:231], v[232:233], off offset:256
	s_cmpk_gt_u32 s35, 0xff
	s_cbranch_scc1 .Lg248_nox
	s_barrier
	s_nop 0

.Lg359_mid:
	ds_read_b128 v[128:131], v150
	ds_read_b128 v[132:135], v150 offset:1024
	ds_read_b128 v[136:139], v150 offset:2048
	ds_read_b128 v[166:169], v150 offset:3072
	s_add_u32 s40, s40, 0x40000
	s_addc_u32 s41, s41, 0
	s_mov_b32 m0, s52
	ds_read_b128 v[170:173], v182 offset:32768
	ds_read_b128 v[174:177], v182 offset:33792
	ds_read_b128 v[192:195], v182 offset:34816
	ds_read_b128 v[196:199], v182 offset:35840
	ds_read_b128 v[200:203], v182 offset:36864
	ds_read_b128 v[204:207], v182 offset:37888
	ds_read_b128 v[208:211], v182 offset:38912
	ds_read_b128 v[212:215], v182 offset:39936
	global_load_lds_dwordx4 v142, s[40:41]
	s_mov_b32 m0, s53
	s_nop 0
	global_load_lds_dwordx4 v146, s[40:41]
	s_waitcnt lgkmcnt(8)
	s_barrier
	s_waitcnt lgkmcnt(0)
	s_waitcnt lgkmcnt(0)
	v_mfma_f32_16x16x32_bf16 v[124:127], v[128:131], v[170:173], v[124:127]
	v_mfma_f32_16x16x32_bf16 v[116:119], v[136:139], v[170:173], v[116:119]
	v_mfma_f32_16x16x32_bf16 v[108:111], v[128:131], v[192:195], v[108:111]
	v_mfma_f32_16x16x32_bf16 v[100:103], v[136:139], v[192:195], v[100:103]
	v_mfma_f32_16x16x32_bf16 v[92:95], v[128:131], v[200:203], v[92:95]
	v_mfma_f32_16x16x32_bf16 v[84:87], v[136:139], v[200:203], v[84:87]
	v_mfma_f32_16x16x32_bf16 v[76:79], v[128:131], v[208:211], v[76:79]
	v_mfma_f32_16x16x32_bf16 v[68:71], v[136:139], v[208:211], v[68:71]
	v_mfma_f32_16x16x32_bf16 v[124:127], v[132:135], v[174:177], v[124:127]
	v_mfma_f32_16x16x32_bf16 v[116:119], v[166:169], v[174:177], v[116:119]
	v_mfma_f32_16x16x32_bf16 v[108:111], v[132:135], v[196:199], v[108:111]
	v_mfma_f32_16x16x32_bf16 v[100:103], v[166:169], v[196:199], v[100:103]
	v_mfma_f32_16x16x32_bf16 v[92:95], v[132:135], v[204:207], v[92:95]
	v_mfma_f32_16x16x32_bf16 v[84:87], v[166:169], v[204:207], v[84:87]
	v_mfma_f32_16x16x32_bf16 v[76:79], v[132:135], v[212:215], v[76:79]
	v_mfma_f32_16x16x32_bf16 v[68:71], v[166:169], v[212:215], v[68:71]
	s_barrier
	s_add_i32 s40, 0, 0x1c000
	s_add_i32 s41, s76, s46
	v_add_u32_e32 v150, s40, v179
	s_mov_b32 m0, s41
	ds_read_b128 v[216:219], v150
	ds_read_b128 v[220:223], v150 offset:1024
	ds_read_b128 v[224:227], v150 offset:2048
	ds_read_b128 v[228:231], v150 offset:3072
	global_load_lds_dwordx4 v144, s[80:81]
	s_add_i32 m0, s41, 0x2000
	s_nop 0
	global_load_lds_dwordx4 v148, s[80:81]
	s_waitcnt vmcnt(10)
	s_barrier
	s_waitcnt lgkmcnt(0)
	s_waitcnt lgkmcnt(0)
	v_mfma_f32_16x16x32_bf16 v[120:123], v[216:219], v[170:173], v[120:123]
	v_mfma_f32_16x16x32_bf16 v[112:115], v[224:227], v[170:173], v[112:115]
	v_mfma_f32_16x16x32_bf16 v[104:107], v[216:219], v[192:195], v[104:107]
	v_mfma_f32_16x16x32_bf16 v[96:99], v[224:227], v[192:195], v[96:99]
	v_mfma_f32_16x16x32_bf16 v[88:91], v[216:219], v[200:203], v[88:91]
	v_mfma_f32_16x16x32_bf16 v[80:83], v[224:227], v[200:203], v[80:83]
	v_mfma_f32_16x16x32_bf16 v[72:75], v[216:219], v[208:211], v[72:75]
	v_mfma_f32_16x16x32_bf16 v[64:67], v[224:227], v[208:211], v[64:67]
	v_mfma_f32_16x16x32_bf16 v[120:123], v[220:223], v[174:177], v[120:123]
	v_mfma_f32_16x16x32_bf16 v[112:115], v[228:231], v[174:177], v[112:115]
	v_mfma_f32_16x16x32_bf16 v[104:107], v[220:223], v[196:199], v[104:107]
	v_mfma_f32_16x16x32_bf16 v[96:99], v[228:231], v[196:199], v[96:99]
	v_mfma_f32_16x16x32_bf16 v[88:91], v[220:223], v[204:207], v[88:91]
	v_mfma_f32_16x16x32_bf16 v[80:83], v[228:231], v[204:207], v[80:83]
	v_mfma_f32_16x16x32_bf16 v[72:75], v[220:223], v[212:215], v[72:75]
	v_mfma_f32_16x16x32_bf16 v[64:67], v[228:231], v[212:215], v[64:67]
	s_mov_b32 m0, s55
	s_barrier
	ds_read_b128 v[170:173], v182 offset:49152
	ds_read_b128 v[174:177], v182 offset:50176
	ds_read_b128 v[192:195], v182 offset:51200
	ds_read_b128 v[196:199], v182 offset:52224
	ds_read_b128 v[200:203], v182 offset:53248
	ds_read_b128 v[204:207], v182 offset:54272
	ds_read_b128 v[208:211], v182 offset:55296
	ds_read_b128 v[212:215], v182 offset:56320
	global_load_lds_dwordx4 v142, s[82:83]
	s_mov_b32 m0, s56
	s_nop 0
	global_load_lds_dwordx4 v146, s[82:83]
	s_barrier
	s_waitcnt lgkmcnt(0)
	s_waitcnt lgkmcnt(0)
	v_mfma_f32_16x16x32_bf16 v[60:63], v[128:131], v[170:173], v[60:63]
	v_mfma_f32_16x16x32_bf16 v[52:55], v[136:139], v[170:173], v[52:55]
	v_mfma_f32_16x16x32_bf16 v[44:47], v[128:131], v[192:195], v[44:47]
	v_mfma_f32_16x16x32_bf16 v[36:39], v[136:139], v[192:195], v[36:39]
	v_mfma_f32_16x16x32_bf16 v[28:31], v[128:131], v[200:203], v[28:31]
	v_mfma_f32_16x16x32_bf16 v[20:23], v[136:139], v[200:203], v[20:23]
	v_mfma_f32_16x16x32_bf16 v[12:15], v[128:131], v[208:211], v[12:15]
	v_mfma_f32_16x16x32_bf16 v[4:7], v[136:139], v[208:211], v[4:7]
	v_mfma_f32_16x16x32_bf16 v[60:63], v[132:135], v[174:177], v[60:63]
	v_mfma_f32_16x16x32_bf16 v[52:55], v[166:169], v[174:177], v[52:55]
	v_mfma_f32_16x16x32_bf16 v[44:47], v[132:135], v[196:199], v[44:47]
	v_mfma_f32_16x16x32_bf16 v[36:39], v[166:169], v[196:199], v[36:39]
	v_mfma_f32_16x16x32_bf16 v[28:31], v[132:135], v[204:207], v[28:31]
	v_mfma_f32_16x16x32_bf16 v[20:23], v[166:169], v[204:207], v[20:23]
	v_mfma_f32_16x16x32_bf16 v[12:15], v[132:135], v[212:215], v[12:15]
	v_mfma_f32_16x16x32_bf16 v[4:7], v[166:169], v[212:215], v[4:7]
	s_barrier
	s_add_u32 s38, s38, 0x40080
	s_addc_u32 s39, s39, 0
	s_add_i32 s40, s40, s46
	s_mov_b32 m0, s40
	s_nop 0
	global_load_lds_dwordx4 v144, s[38:39]
	s_add_i32 m0, s40, 0x2000
	s_nop 0
	global_load_lds_dwordx4 v148, s[38:39]
	s_waitcnt vmcnt(8)
	s_barrier
	v_mfma_f32_16x16x32_bf16 v[56:59], v[216:219], v[170:173], v[56:59]
	v_mfma_f32_16x16x32_bf16 v[48:51], v[224:227], v[170:173], v[48:51]
	v_mfma_f32_16x16x32_bf16 v[40:43], v[216:219], v[192:195], v[40:43]
	v_mfma_f32_16x16x32_bf16 v[32:35], v[224:227], v[192:195], v[32:35]
	v_mfma_f32_16x16x32_bf16 v[24:27], v[216:219], v[200:203], v[24:27]
	v_mfma_f32_16x16x32_bf16 v[16:19], v[224:227], v[200:203], v[16:19]
	v_mfma_f32_16x16x32_bf16 v[8:11], v[216:219], v[208:211], v[8:11]
	v_mfma_f32_16x16x32_bf16 v[0:3], v[224:227], v[208:211], v[0:3]
	v_mfma_f32_16x16x32_bf16 v[56:59], v[220:223], v[174:177], v[56:59]
	v_mfma_f32_16x16x32_bf16 v[48:51], v[228:231], v[174:177], v[48:51]
	v_mfma_f32_16x16x32_bf16 v[40:43], v[220:223], v[196:199], v[40:43]
	v_mfma_f32_16x16x32_bf16 v[32:35], v[228:231], v[196:199], v[32:35]
	v_mfma_f32_16x16x32_bf16 v[24:27], v[220:223], v[204:207], v[24:27]
	v_mfma_f32_16x16x32_bf16 v[16:19], v[228:231], v[204:207], v[16:19]
	v_mfma_f32_16x16x32_bf16 v[8:11], v[220:223], v[212:215], v[8:11]
	v_mfma_f32_16x16x32_bf16 v[0:3], v[228:231], v[212:215], v[0:3]
	s_add_i32 s75, s75, 2
	s_add_u32 s8, s8, 0x100
	s_addc_u32 s9, s9, 0
	s_add_u32 s73, s73, 0x100
	s_addc_u32 s74, s74, 0
	s_cmp_gt_u32 s75, 13
	s_barrier
	s_cbranch_scc0 .LBB0_359
	s_setprio 0
	s_cmpk_gt_u32 s45, 0xff
	s_cbranch_scc1 .Lg359_nox
	s_barrier
	s_nop 0

.Lg786_mid:
	ds_read_b128 v[144:147], v155
	ds_read_b128 v[156:159], v155 offset:1024
	ds_read_b128 v[160:163], v155 offset:2048
	ds_read_b128 v[164:167], v155 offset:3072
	s_add_u32 s34, s34, 0x40000
	s_addc_u32 s35, s35, 0
	s_mov_b32 m0, s47
	ds_read_b128 v[168:171], v152 offset:32768
	ds_read_b128 v[172:175], v152 offset:33792
	ds_read_b128 v[176:179], v152 offset:34816
	ds_read_b128 v[180:183], v152 offset:35840
	ds_read_b128 v[184:187], v152 offset:36864
	ds_read_b128 v[188:191], v152 offset:37888
	ds_read_b128 v[192:195], v152 offset:38912
	ds_read_b128 v[196:199], v152 offset:39936
	global_load_lds_dwordx4 v134, s[34:35]
	s_mov_b32 m0, s48
	s_nop 0
	global_load_lds_dwordx4 v130, s[34:35]
	s_waitcnt lgkmcnt(8)
	s_barrier
	s_waitcnt lgkmcnt(0)
	s_waitcnt lgkmcnt(0)
	v_mfma_f32_16x16x32_bf16 v[124:127], v[144:147], v[168:171], v[124:127]
	v_mfma_f32_16x16x32_bf16 v[120:123], v[160:163], v[168:171], v[120:123]
	v_mfma_f32_16x16x32_bf16 v[108:111], v[144:147], v[176:179], v[108:111]
	v_mfma_f32_16x16x32_bf16 v[104:107], v[160:163], v[176:179], v[104:107]
	v_mfma_f32_16x16x32_bf16 v[92:95], v[144:147], v[184:187], v[92:95]
	v_mfma_f32_16x16x32_bf16 v[88:91], v[160:163], v[184:187], v[88:91]
	v_mfma_f32_16x16x32_bf16 v[76:79], v[144:147], v[192:195], v[76:79]
	v_mfma_f32_16x16x32_bf16 v[72:75], v[160:163], v[192:195], v[72:75]
	v_mfma_f32_16x16x32_bf16 v[124:127], v[156:159], v[172:175], v[124:127]
	v_mfma_f32_16x16x32_bf16 v[120:123], v[164:167], v[172:175], v[120:123]
	v_mfma_f32_16x16x32_bf16 v[108:111], v[156:159], v[180:183], v[108:111]
	v_mfma_f32_16x16x32_bf16 v[104:107], v[164:167], v[180:183], v[104:107]
	v_mfma_f32_16x16x32_bf16 v[92:95], v[156:159], v[188:191], v[92:95]
	v_mfma_f32_16x16x32_bf16 v[88:91], v[164:167], v[188:191], v[88:91]
	v_mfma_f32_16x16x32_bf16 v[76:79], v[156:159], v[196:199], v[76:79]
	v_mfma_f32_16x16x32_bf16 v[72:75], v[164:167], v[196:199], v[72:75]
	s_barrier
	s_add_i32 s34, 0, 0x1c000
	s_add_i32 s35, s62, s42
	v_add_u32_e32 v155, s34, v149
	s_mov_b32 m0, s35
	ds_read_b128 v[200:203], v155
	ds_read_b128 v[204:207], v155 offset:1024
	ds_read_b128 v[208:211], v155 offset:2048
	ds_read_b128 v[212:215], v155 offset:3072
	global_load_lds_dwordx4 v132, s[80:81]
	s_add_i32 m0, s35, 0x2000
	s_nop 0
	global_load_lds_dwordx4 v128, s[80:81]
	s_waitcnt vmcnt(10)
	s_barrier
	s_waitcnt lgkmcnt(0)
	s_waitcnt lgkmcnt(0)
	v_mfma_f32_16x16x32_bf16 v[116:119], v[200:203], v[168:171], v[116:119]
	v_mfma_f32_16x16x32_bf16 v[112:115], v[208:211], v[168:171], v[112:115]
	v_mfma_f32_16x16x32_bf16 v[100:103], v[200:203], v[176:179], v[100:103]
	v_mfma_f32_16x16x32_bf16 v[96:99], v[208:211], v[176:179], v[96:99]
	v_mfma_f32_16x16x32_bf16 v[84:87], v[200:203], v[184:187], v[84:87]
	v_mfma_f32_16x16x32_bf16 v[80:83], v[208:211], v[184:187], v[80:83]
	v_mfma_f32_16x16x32_bf16 v[68:71], v[200:203], v[192:195], v[68:71]
	v_mfma_f32_16x16x32_bf16 v[64:67], v[208:211], v[192:195], v[64:67]
	v_mfma_f32_16x16x32_bf16 v[116:119], v[204:207], v[172:175], v[116:119]
	v_mfma_f32_16x16x32_bf16 v[112:115], v[212:215], v[172:175], v[112:115]
	v_mfma_f32_16x16x32_bf16 v[100:103], v[204:207], v[180:183], v[100:103]
	v_mfma_f32_16x16x32_bf16 v[96:99], v[212:215], v[180:183], v[96:99]
	v_mfma_f32_16x16x32_bf16 v[84:87], v[204:207], v[188:191], v[84:87]
	v_mfma_f32_16x16x32_bf16 v[80:83], v[212:215], v[188:191], v[80:83]
	v_mfma_f32_16x16x32_bf16 v[68:71], v[204:207], v[196:199], v[68:71]
	v_mfma_f32_16x16x32_bf16 v[64:67], v[212:215], v[196:199], v[64:67]
	s_mov_b32 m0, s50
	s_barrier
	ds_read_b128 v[168:171], v152 offset:49152
	ds_read_b128 v[172:175], v152 offset:50176
	ds_read_b128 v[176:179], v152 offset:51200
	ds_read_b128 v[180:183], v152 offset:52224
	ds_read_b128 v[184:187], v152 offset:53248
	ds_read_b128 v[188:191], v152 offset:54272
	ds_read_b128 v[192:195], v152 offset:55296
	ds_read_b128 v[196:199], v152 offset:56320
	global_load_lds_dwordx4 v134, s[82:83]
	s_mov_b32 m0, s51
	s_nop 0
	global_load_lds_dwordx4 v130, s[82:83]
	s_barrier
	s_waitcnt lgkmcnt(0)
	s_waitcnt lgkmcnt(0)
	v_mfma_f32_16x16x32_bf16 v[60:63], v[144:147], v[168:171], v[60:63]
	v_mfma_f32_16x16x32_bf16 v[56:59], v[160:163], v[168:171], v[56:59]
	v_mfma_f32_16x16x32_bf16 v[44:47], v[144:147], v[176:179], v[44:47]
	v_mfma_f32_16x16x32_bf16 v[40:43], v[160:163], v[176:179], v[40:43]
	v_mfma_f32_16x16x32_bf16 v[28:31], v[144:147], v[184:187], v[28:31]
	v_mfma_f32_16x16x32_bf16 v[24:27], v[160:163], v[184:187], v[24:27]
	v_mfma_f32_16x16x32_bf16 v[12:15], v[144:147], v[192:195], v[12:15]
	v_mfma_f32_16x16x32_bf16 v[8:11], v[160:163], v[192:195], v[8:11]
	v_mfma_f32_16x16x32_bf16 v[60:63], v[156:159], v[172:175], v[60:63]
	v_mfma_f32_16x16x32_bf16 v[56:59], v[164:167], v[172:175], v[56:59]
	v_mfma_f32_16x16x32_bf16 v[44:47], v[156:159], v[180:183], v[44:47]
	v_mfma_f32_16x16x32_bf16 v[40:43], v[164:167], v[180:183], v[40:43]
	v_mfma_f32_16x16x32_bf16 v[28:31], v[156:159], v[188:191], v[28:31]
	v_mfma_f32_16x16x32_bf16 v[24:27], v[164:167], v[188:191], v[24:27]
	v_mfma_f32_16x16x32_bf16 v[12:15], v[156:159], v[196:199], v[12:15]
	v_mfma_f32_16x16x32_bf16 v[8:11], v[164:167], v[196:199], v[8:11]
	s_barrier
	s_add_u32 s30, s30, 0x40080
	s_addc_u32 s31, s31, 0
	s_add_i32 s34, s34, s42
	s_mov_b32 m0, s34
	s_nop 0
	global_load_lds_dwordx4 v132, s[30:31]
	s_add_i32 m0, s34, 0x2000
	s_nop 0
	global_load_lds_dwordx4 v128, s[30:31]
	s_waitcnt vmcnt(8)
	s_barrier
	v_mfma_f32_16x16x32_bf16 v[52:55], v[200:203], v[168:171], v[52:55]
	v_mfma_f32_16x16x32_bf16 v[48:51], v[208:211], v[168:171], v[48:51]
	v_mfma_f32_16x16x32_bf16 v[36:39], v[200:203], v[176:179], v[36:39]
	v_mfma_f32_16x16x32_bf16 v[32:35], v[208:211], v[176:179], v[32:35]
	v_mfma_f32_16x16x32_bf16 v[20:23], v[200:203], v[184:187], v[20:23]
	v_mfma_f32_16x16x32_bf16 v[16:19], v[208:211], v[184:187], v[16:19]
	v_mfma_f32_16x16x32_bf16 v[4:7], v[200:203], v[192:195], v[4:7]
	v_mfma_f32_16x16x32_bf16 v[0:3], v[208:211], v[192:195], v[0:3]
	v_mfma_f32_16x16x32_bf16 v[52:55], v[204:207], v[172:175], v[52:55]
	v_mfma_f32_16x16x32_bf16 v[48:51], v[212:215], v[172:175], v[48:51]
	v_mfma_f32_16x16x32_bf16 v[36:39], v[204:207], v[180:183], v[36:39]
	v_mfma_f32_16x16x32_bf16 v[32:35], v[212:215], v[180:183], v[32:35]
	v_mfma_f32_16x16x32_bf16 v[20:23], v[204:207], v[188:191], v[20:23]
	v_mfma_f32_16x16x32_bf16 v[16:19], v[212:215], v[188:191], v[16:19]
	v_mfma_f32_16x16x32_bf16 v[4:7], v[204:207], v[196:199], v[4:7]
	v_mfma_f32_16x16x32_bf16 v[0:3], v[212:215], v[196:199], v[0:3]
	s_add_i32 s61, s61, 2
	s_add_u32 s28, s28, 0x100
	s_addc_u32 s29, s29, 0
	s_add_u32 s59, s59, 0x100
	s_addc_u32 s60, s60, 0
	s_cmp_gt_u32 s61, 13
	s_barrier
	s_cbranch_scc0 .LBB0_786
	s_setprio 0
	v_lshl_add_u32 v146, s8, 8, v148
	v_ashrrev_i32_e32 v147, 31, v146
	v_lshl_or_b32 v144, s56, 8, v150
	v_lshlrev_b64 v[156:157], 11, v[146:147]
	v_ashrrev_i32_e32 v145, 31, v144
	v_lshl_add_u64 v[156:157], s[10:11], 0, v[156:157]
	v_lshl_add_u64 v[166:167], v[144:145], 1, v[156:157]
	global_load_dwordx4 v[158:161], v[166:167], off
	global_load_dwordx4 v[162:165], v[166:167], off offset:256
	s_mov_b64 s[84:85], 0x8000
	s_mov_b64 s[86:87], 0x28000
	v_lshl_add_u64 v[232:233], v[166:167], 0, s[84:85]
	global_load_dwordx4 v[176:179], v[232:233], off
	global_load_dwordx4 v[180:183], v[232:233], off offset:256
	v_lshl_add_u64 v[232:233], v[232:233], 0, s[84:85]
	global_load_dwordx4 v[184:187], v[232:233], off
	global_load_dwordx4 v[188:191], v[232:233], off offset:256
	v_lshl_add_u64 v[232:233], v[232:233], 0, s[84:85]
	global_load_dwordx4 v[192:195], v[232:233], off
	global_load_dwordx4 v[196:199], v[232:233], off offset:256
	v_lshl_add_u64 v[232:233], v[232:233], 0, s[86:87]
	global_load_dwordx4 v[200:203], v[232:233], off
	global_load_dwordx4 v[204:207], v[232:233], off offset:256
	v_lshl_add_u64 v[232:233], v[232:233], 0, s[84:85]
	global_load_dwordx4 v[208:211], v[232:233], off
	global_load_dwordx4 v[212:215], v[232:233], off offset:256
	v_lshl_add_u64 v[232:233], v[232:233], 0, s[84:85]
	global_load_dwordx4 v[216:219], v[232:233], off
	global_load_dwordx4 v[220:223], v[232:233], off offset:256
	v_lshl_add_u64 v[232:233], v[232:233], 0, s[84:85]
	global_load_dwordx4 v[224:227], v[232:233], off
	global_load_dwordx4 v[228:231], v[232:233], off offset:256
	s_cmpk_gt_u32 s37, 0xff
	s_cbranch_scc1 .Lg786_nox
	s_barrier
	s_nop 0

.Lg893_mid:
	ds_read_b128 v[152:155], v151
	ds_read_b128 v[156:159], v151 offset:1024
	ds_read_b128 v[160:163], v151 offset:2048
	ds_read_b128 v[164:167], v151 offset:3072
	s_add_u32 s28, s28, 0x40000
	s_addc_u32 s29, s29, 0
	s_mov_b32 m0, s43
	ds_read_b128 v[168:171], v149 offset:32768
	ds_read_b128 v[172:175], v149 offset:33792
	ds_read_b128 v[176:179], v149 offset:34816
	ds_read_b128 v[180:183], v149 offset:35840
	ds_read_b128 v[184:187], v149 offset:36864
	ds_read_b128 v[188:191], v149 offset:37888
	ds_read_b128 v[192:195], v149 offset:38912
	ds_read_b128 v[196:199], v149 offset:39936
	global_load_lds_dwordx4 v134, s[28:29]
	s_mov_b32 m0, s44
	s_nop 0
	global_load_lds_dwordx4 v130, s[28:29]
	s_waitcnt lgkmcnt(8)
	s_barrier
	s_waitcnt lgkmcnt(0)
	s_waitcnt lgkmcnt(0)
	v_mfma_f32_16x16x32_bf16 v[124:127], v[152:155], v[168:171], v[124:127]
	v_mfma_f32_16x16x32_bf16 v[120:123], v[160:163], v[168:171], v[120:123]
	v_mfma_f32_16x16x32_bf16 v[108:111], v[152:155], v[176:179], v[108:111]
	v_mfma_f32_16x16x32_bf16 v[104:107], v[160:163], v[176:179], v[104:107]
	v_mfma_f32_16x16x32_bf16 v[92:95], v[152:155], v[184:187], v[92:95]
	v_mfma_f32_16x16x32_bf16 v[88:91], v[160:163], v[184:187], v[88:91]
	v_mfma_f32_16x16x32_bf16 v[76:79], v[152:155], v[192:195], v[76:79]
	v_mfma_f32_16x16x32_bf16 v[72:75], v[160:163], v[192:195], v[72:75]
	v_mfma_f32_16x16x32_bf16 v[124:127], v[156:159], v[172:175], v[124:127]
	v_mfma_f32_16x16x32_bf16 v[120:123], v[164:167], v[172:175], v[120:123]
	v_mfma_f32_16x16x32_bf16 v[108:111], v[156:159], v[180:183], v[108:111]
	v_mfma_f32_16x16x32_bf16 v[104:107], v[164:167], v[180:183], v[104:107]
	v_mfma_f32_16x16x32_bf16 v[92:95], v[156:159], v[188:191], v[92:95]
	v_mfma_f32_16x16x32_bf16 v[88:91], v[164:167], v[188:191], v[88:91]
	v_mfma_f32_16x16x32_bf16 v[76:79], v[156:159], v[196:199], v[76:79]
	v_mfma_f32_16x16x32_bf16 v[72:75], v[164:167], v[196:199], v[72:75]
	s_barrier
	s_add_i32 s28, 0, 0x1c000
	s_add_i32 s29, s58, s31
	v_add_u32_e32 v151, s28, v145
	s_mov_b32 m0, s29
	ds_read_b128 v[200:203], v151
	ds_read_b128 v[204:207], v151 offset:1024
	ds_read_b128 v[208:211], v151 offset:2048
	ds_read_b128 v[212:215], v151 offset:3072
	global_load_lds_dwordx4 v132, s[80:81]
	s_add_i32 m0, s29, 0x2000
	s_nop 0
	global_load_lds_dwordx4 v128, s[80:81]
	s_waitcnt vmcnt(10)
	s_barrier
	s_waitcnt lgkmcnt(0)
	s_waitcnt lgkmcnt(0)
	v_mfma_f32_16x16x32_bf16 v[116:119], v[200:203], v[168:171], v[116:119]
	v_mfma_f32_16x16x32_bf16 v[112:115], v[208:211], v[168:171], v[112:115]
	v_mfma_f32_16x16x32_bf16 v[100:103], v[200:203], v[176:179], v[100:103]
	v_mfma_f32_16x16x32_bf16 v[96:99], v[208:211], v[176:179], v[96:99]
	v_mfma_f32_16x16x32_bf16 v[84:87], v[200:203], v[184:187], v[84:87]
	v_mfma_f32_16x16x32_bf16 v[80:83], v[208:211], v[184:187], v[80:83]
	v_mfma_f32_16x16x32_bf16 v[68:71], v[200:203], v[192:195], v[68:71]
	v_mfma_f32_16x16x32_bf16 v[64:67], v[208:211], v[192:195], v[64:67]
	v_mfma_f32_16x16x32_bf16 v[116:119], v[204:207], v[172:175], v[116:119]
	v_mfma_f32_16x16x32_bf16 v[112:115], v[212:215], v[172:175], v[112:115]
	v_mfma_f32_16x16x32_bf16 v[100:103], v[204:207], v[180:183], v[100:103]
	v_mfma_f32_16x16x32_bf16 v[96:99], v[212:215], v[180:183], v[96:99]
	v_mfma_f32_16x16x32_bf16 v[84:87], v[204:207], v[188:191], v[84:87]
	v_mfma_f32_16x16x32_bf16 v[80:83], v[212:215], v[188:191], v[80:83]
	v_mfma_f32_16x16x32_bf16 v[68:71], v[204:207], v[196:199], v[68:71]
	v_mfma_f32_16x16x32_bf16 v[64:67], v[212:215], v[196:199], v[64:67]
	s_mov_b32 m0, s45
	s_barrier
	ds_read_b128 v[168:171], v149 offset:49152
	ds_read_b128 v[172:175], v149 offset:50176
	ds_read_b128 v[176:179], v149 offset:51200
	ds_read_b128 v[180:183], v149 offset:52224
	ds_read_b128 v[184:187], v149 offset:53248
	ds_read_b128 v[188:191], v149 offset:54272
	ds_read_b128 v[192:195], v149 offset:55296
	ds_read_b128 v[196:199], v149 offset:56320
	global_load_lds_dwordx4 v134, s[82:83]
	s_mov_b32 m0, s46
	s_nop 0
	global_load_lds_dwordx4 v130, s[82:83]
	s_barrier
	s_waitcnt lgkmcnt(0)
	s_waitcnt lgkmcnt(0)
	v_mfma_f32_16x16x32_bf16 v[60:63], v[152:155], v[168:171], v[60:63]
	v_mfma_f32_16x16x32_bf16 v[56:59], v[160:163], v[168:171], v[56:59]
	v_mfma_f32_16x16x32_bf16 v[44:47], v[152:155], v[176:179], v[44:47]
	v_mfma_f32_16x16x32_bf16 v[40:43], v[160:163], v[176:179], v[40:43]
	v_mfma_f32_16x16x32_bf16 v[28:31], v[152:155], v[184:187], v[28:31]
	v_mfma_f32_16x16x32_bf16 v[24:27], v[160:163], v[184:187], v[24:27]
	v_mfma_f32_16x16x32_bf16 v[12:15], v[152:155], v[192:195], v[12:15]
	v_mfma_f32_16x16x32_bf16 v[8:11], v[160:163], v[192:195], v[8:11]
	v_mfma_f32_16x16x32_bf16 v[60:63], v[156:159], v[172:175], v[60:63]
	v_mfma_f32_16x16x32_bf16 v[56:59], v[164:167], v[172:175], v[56:59]
	v_mfma_f32_16x16x32_bf16 v[44:47], v[156:159], v[180:183], v[44:47]
	v_mfma_f32_16x16x32_bf16 v[40:43], v[164:167], v[180:183], v[40:43]
	v_mfma_f32_16x16x32_bf16 v[28:31], v[156:159], v[188:191], v[28:31]
	v_mfma_f32_16x16x32_bf16 v[24:27], v[164:167], v[188:191], v[24:27]
	v_mfma_f32_16x16x32_bf16 v[12:15], v[156:159], v[196:199], v[12:15]
	v_mfma_f32_16x16x32_bf16 v[8:11], v[164:167], v[196:199], v[8:11]
	s_barrier
	s_add_u32 s26, s26, 0x40080
	s_addc_u32 s27, s27, 0
	s_add_i32 s28, s28, s31
	s_mov_b32 m0, s28
	s_nop 0
	global_load_lds_dwordx4 v132, s[26:27]
	s_add_i32 m0, s28, 0x2000
	s_nop 0
	global_load_lds_dwordx4 v128, s[26:27]
	s_waitcnt vmcnt(8)
	s_barrier
	v_mfma_f32_16x16x32_bf16 v[52:55], v[200:203], v[168:171], v[52:55]
	v_mfma_f32_16x16x32_bf16 v[48:51], v[208:211], v[168:171], v[48:51]
	v_mfma_f32_16x16x32_bf16 v[36:39], v[200:203], v[176:179], v[36:39]
	v_mfma_f32_16x16x32_bf16 v[32:35], v[208:211], v[176:179], v[32:35]
	v_mfma_f32_16x16x32_bf16 v[20:23], v[200:203], v[184:187], v[20:23]
	v_mfma_f32_16x16x32_bf16 v[16:19], v[208:211], v[184:187], v[16:19]
	v_mfma_f32_16x16x32_bf16 v[4:7], v[200:203], v[192:195], v[4:7]
	v_mfma_f32_16x16x32_bf16 v[0:3], v[208:211], v[192:195], v[0:3]
	v_mfma_f32_16x16x32_bf16 v[52:55], v[204:207], v[172:175], v[52:55]
	v_mfma_f32_16x16x32_bf16 v[48:51], v[212:215], v[172:175], v[48:51]
	v_mfma_f32_16x16x32_bf16 v[36:39], v[204:207], v[180:183], v[36:39]
	v_mfma_f32_16x16x32_bf16 v[32:35], v[212:215], v[180:183], v[32:35]
	v_mfma_f32_16x16x32_bf16 v[20:23], v[204:207], v[188:191], v[20:23]
	v_mfma_f32_16x16x32_bf16 v[16:19], v[212:215], v[188:191], v[16:19]
	v_mfma_f32_16x16x32_bf16 v[4:7], v[204:207], v[196:199], v[4:7]
	v_mfma_f32_16x16x32_bf16 v[0:3], v[212:215], v[196:199], v[0:3]
	s_add_i32 s57, s57, 2
	s_add_u32 s20, s20, 0x100
	s_addc_u32 s21, s21, 0
	s_add_u32 s55, s55, 0x100
	s_addc_u32 s56, s56, 0
	s_cmp_gt_u32 s57, 13
	s_barrier
	s_cbranch_scc0 .LBB0_893
	s_setprio 0
	s_cmpk_gt_u32 s30, 0xff
	s_cbranch_scc1 .Lg893_nox
	s_barrier
	s_nop 0

.Lg973_mid:
	ds_read_b128 v[146:149], v158
	ds_read_b128 v[150:153], v158 offset:1024
	ds_read_b128 v[154:157], v158 offset:2048
	ds_read_b128 v[158:161], v158 offset:3072
	s_add_u32 s20, s26, 0xb0000
	s_addc_u32 s21, s27, 0
	s_mov_b32 m0, s39
	ds_read_b128 v[162:165], v204 offset:32768
	ds_read_b128 v[166:169], v204 offset:33792
	ds_read_b128 v[170:173], v204 offset:34816
	ds_read_b128 v[174:177], v204 offset:35840
	ds_read_b128 v[178:181], v204 offset:36864
	ds_read_b128 v[182:185], v204 offset:37888
	ds_read_b128 v[186:189], v204 offset:38912
	ds_read_b128 v[190:193], v204 offset:39936
	global_load_lds_dwordx4 v128, s[20:21]
	s_mov_b32 m0, s40
	s_nop 0
	global_load_lds_dwordx4 v132, s[20:21]
	s_waitcnt lgkmcnt(8)
	s_barrier
	s_waitcnt lgkmcnt(0)
	s_waitcnt lgkmcnt(0)
	v_mfma_f32_16x16x32_bf16 v[124:127], v[146:149], v[162:165], v[124:127]
	v_mfma_f32_16x16x32_bf16 v[120:123], v[154:157], v[162:165], v[120:123]
	v_mfma_f32_16x16x32_bf16 v[108:111], v[146:149], v[170:173], v[108:111]
	v_mfma_f32_16x16x32_bf16 v[104:107], v[154:157], v[170:173], v[104:107]
	v_mfma_f32_16x16x32_bf16 v[92:95], v[146:149], v[178:181], v[92:95]
	v_mfma_f32_16x16x32_bf16 v[88:91], v[154:157], v[178:181], v[88:91]
	v_mfma_f32_16x16x32_bf16 v[76:79], v[146:149], v[186:189], v[76:79]
	v_mfma_f32_16x16x32_bf16 v[72:75], v[154:157], v[186:189], v[72:75]
	v_mfma_f32_16x16x32_bf16 v[124:127], v[150:153], v[166:169], v[124:127]
	v_mfma_f32_16x16x32_bf16 v[120:123], v[158:161], v[166:169], v[120:123]
	v_mfma_f32_16x16x32_bf16 v[108:111], v[150:153], v[174:177], v[108:111]
	v_mfma_f32_16x16x32_bf16 v[104:107], v[158:161], v[174:177], v[104:107]
	v_mfma_f32_16x16x32_bf16 v[92:95], v[150:153], v[182:185], v[92:95]
	v_mfma_f32_16x16x32_bf16 v[88:91], v[158:161], v[182:185], v[88:91]
	v_mfma_f32_16x16x32_bf16 v[76:79], v[150:153], v[190:193], v[76:79]
	v_mfma_f32_16x16x32_bf16 v[72:75], v[158:161], v[190:193], v[72:75]
	s_barrier
	s_add_i32 s26, 0, 0x1c000
	s_add_i32 s20, s57, s36
	v_add_u32_e32 v216, s26, v201
	s_mov_b32 m0, s20
	ds_read_b128 v[194:197], v216
	ds_read_b128 v[208:211], v216 offset:1024
	ds_read_b128 v[212:215], v216 offset:2048
	ds_read_b128 v[216:219], v216 offset:3072
	global_load_lds_dwordx4 v130, s[80:81]
	s_add_i32 m0, s20, 0x2000
	s_nop 0
	global_load_lds_dwordx4 v134, s[80:81]
	s_waitcnt vmcnt(10)
	s_barrier
	s_waitcnt lgkmcnt(0)
	s_waitcnt lgkmcnt(0)
	v_mfma_f32_16x16x32_bf16 v[116:119], v[194:197], v[162:165], v[116:119]
	v_mfma_f32_16x16x32_bf16 v[112:115], v[212:215], v[162:165], v[112:115]
	v_mfma_f32_16x16x32_bf16 v[100:103], v[194:197], v[170:173], v[100:103]
	v_mfma_f32_16x16x32_bf16 v[96:99], v[212:215], v[170:173], v[96:99]
	v_mfma_f32_16x16x32_bf16 v[84:87], v[194:197], v[178:181], v[84:87]
	v_mfma_f32_16x16x32_bf16 v[80:83], v[212:215], v[178:181], v[80:83]
	v_mfma_f32_16x16x32_bf16 v[68:71], v[194:197], v[186:189], v[68:71]
	v_mfma_f32_16x16x32_bf16 v[64:67], v[212:215], v[186:189], v[64:67]
	v_mfma_f32_16x16x32_bf16 v[116:119], v[208:211], v[166:169], v[116:119]
	v_mfma_f32_16x16x32_bf16 v[112:115], v[216:219], v[166:169], v[112:115]
	v_mfma_f32_16x16x32_bf16 v[100:103], v[208:211], v[174:177], v[100:103]
	v_mfma_f32_16x16x32_bf16 v[96:99], v[216:219], v[174:177], v[96:99]
	v_mfma_f32_16x16x32_bf16 v[84:87], v[208:211], v[182:185], v[84:87]
	v_mfma_f32_16x16x32_bf16 v[80:83], v[216:219], v[182:185], v[80:83]
	v_mfma_f32_16x16x32_bf16 v[68:71], v[208:211], v[190:193], v[68:71]
	v_mfma_f32_16x16x32_bf16 v[64:67], v[216:219], v[190:193], v[64:67]
	s_mov_b32 m0, s42
	s_barrier
	ds_read_b128 v[162:165], v204 offset:49152
	ds_read_b128 v[166:169], v204 offset:50176
	ds_read_b128 v[170:173], v204 offset:51200
	ds_read_b128 v[174:177], v204 offset:52224
	ds_read_b128 v[178:181], v204 offset:53248
	ds_read_b128 v[182:185], v204 offset:54272
	ds_read_b128 v[186:189], v204 offset:55296
	ds_read_b128 v[190:193], v204 offset:56320
	global_load_lds_dwordx4 v128, s[82:83]
	s_mov_b32 m0, s43
	s_nop 0
	global_load_lds_dwordx4 v132, s[82:83]
	s_barrier
	s_waitcnt lgkmcnt(0)
	s_waitcnt lgkmcnt(0)
	v_mfma_f32_16x16x32_bf16 v[60:63], v[146:149], v[162:165], v[60:63]
	v_mfma_f32_16x16x32_bf16 v[56:59], v[154:157], v[162:165], v[56:59]
	v_mfma_f32_16x16x32_bf16 v[44:47], v[146:149], v[170:173], v[44:47]
	v_mfma_f32_16x16x32_bf16 v[40:43], v[154:157], v[170:173], v[40:43]
	v_mfma_f32_16x16x32_bf16 v[28:31], v[146:149], v[178:181], v[28:31]
	v_mfma_f32_16x16x32_bf16 v[24:27], v[154:157], v[178:181], v[24:27]
	v_mfma_f32_16x16x32_bf16 v[12:15], v[146:149], v[186:189], v[12:15]
	v_mfma_f32_16x16x32_bf16 v[8:11], v[154:157], v[186:189], v[8:11]
	v_mfma_f32_16x16x32_bf16 v[60:63], v[150:153], v[166:169], v[60:63]
	v_mfma_f32_16x16x32_bf16 v[56:59], v[158:161], v[166:169], v[56:59]
	v_mfma_f32_16x16x32_bf16 v[44:47], v[150:153], v[174:177], v[44:47]
	v_mfma_f32_16x16x32_bf16 v[40:43], v[158:161], v[174:177], v[40:43]
	v_mfma_f32_16x16x32_bf16 v[28:31], v[150:153], v[182:185], v[28:31]
	v_mfma_f32_16x16x32_bf16 v[24:27], v[158:161], v[182:185], v[24:27]
	v_mfma_f32_16x16x32_bf16 v[12:15], v[150:153], v[190:193], v[12:15]
	v_mfma_f32_16x16x32_bf16 v[8:11], v[158:161], v[190:193], v[8:11]
	s_barrier
	s_add_u32 s20, s24, 0xb0080
	s_addc_u32 s21, s25, 0
	s_add_i32 s24, s26, s36
	s_mov_b32 m0, s24
	s_nop 0
	global_load_lds_dwordx4 v130, s[20:21]
	s_add_i32 m0, s24, 0x2000
	s_nop 0
	global_load_lds_dwordx4 v134, s[20:21]
	s_waitcnt vmcnt(8)
	s_barrier
	v_mfma_f32_16x16x32_bf16 v[52:55], v[194:197], v[162:165], v[52:55]
	v_mfma_f32_16x16x32_bf16 v[48:51], v[212:215], v[162:165], v[48:51]
	v_mfma_f32_16x16x32_bf16 v[36:39], v[194:197], v[170:173], v[36:39]
	v_mfma_f32_16x16x32_bf16 v[32:35], v[212:215], v[170:173], v[32:35]
	v_mfma_f32_16x16x32_bf16 v[20:23], v[194:197], v[178:181], v[20:23]
	v_mfma_f32_16x16x32_bf16 v[16:19], v[212:215], v[178:181], v[16:19]
	v_mfma_f32_16x16x32_bf16 v[4:7], v[194:197], v[186:189], v[4:7]
	v_mfma_f32_16x16x32_bf16 v[0:3], v[212:215], v[186:189], v[0:3]
	v_mfma_f32_16x16x32_bf16 v[52:55], v[208:211], v[166:169], v[52:55]
	v_mfma_f32_16x16x32_bf16 v[48:51], v[216:219], v[166:169], v[48:51]
	v_mfma_f32_16x16x32_bf16 v[36:39], v[208:211], v[174:177], v[36:39]
	v_mfma_f32_16x16x32_bf16 v[32:35], v[216:219], v[174:177], v[32:35]
	v_mfma_f32_16x16x32_bf16 v[20:23], v[208:211], v[182:185], v[20:23]
	v_mfma_f32_16x16x32_bf16 v[16:19], v[216:219], v[182:185], v[16:19]
	v_mfma_f32_16x16x32_bf16 v[4:7], v[208:211], v[190:193], v[4:7]
	v_mfma_f32_16x16x32_bf16 v[0:3], v[216:219], v[190:193], v[0:3]
	s_add_i32 s56, s56, 2
	s_add_u32 s54, s54, 0x100
	s_addc_u32 s55, s55, 0
	s_cmp_gt_u32 s56, 41
	s_mov_b64 s[20:21], s[22:23]
	s_barrier
	s_cbranch_scc0 .LBB0_973
	s_setprio 0
	s_cmpk_gt_u32 s30, 0xff
	s_cbranch_scc1 .Lg973_nox
	s_barrier
	s_nop 0
